# CU-slot-aware tail scheduling: gemm1/gemm3 third-round tiles on workgroups that cannot be CU partners
# speedup vs baseline: 1.0076x; 1.0076x over previous
.LBB0_889:
	s_add_i32 s3, s0, s28
	s_cmpk_lt_i32 s3, 0x400
	s_cbranch_scc1 .Ltr_done_889
	s_cmpk_lg_i32 s23, 0x480
	s_cbranch_scc1 .Ltr_done_889
	s_cmpk_lg_i32 s28, 0x200
	s_cbranch_scc1 .Ltr_done_889
	s_add_i32 s1, s3, 0xfffffc00
	s_movk_i32 s3, 0x7fff
	s_cmpk_ge_u32 s1, 0x100
	s_cbranch_scc1 .Ltr_done_889
	s_bitcmp1_b32 s1, 3
	s_cbranch_scc1 .Ltr_done_889
	s_lshr_b32 s19, s1, 4
	s_lshl_b32 s19, s19, 3
	s_and_b32 s1, s1, 7
	s_or_b32 s1, s1, s19
	s_add_i32 s3, s1, 0x400
.Ltr_done_889:
	s_cmp_lt_i32 s3, s23
	s_cselect_b64 s[44:45], -1, 0
	s_cmp_ge_i32 s3, s23
	s_cselect_b64 s[34:35], -1, 0
	s_mov_b64 s[46:47], 0
	s_and_b64 vcc, exec, s[34:35]
	s_mov_b64 s[56:57], 0
	s_mov_b64 s[52:53], 0
	s_cbranch_vccnz .LBB0_891
	s_and_b32 s1, s3, 7
	s_mul_i32 s1, s1, s2
	s_ashr_i32 s19, s3, 3
	s_add_i32 s1, s1, s19
	s_ashr_i32 s19, s1, 31
	s_lshr_b32 s19, s19, 26
	s_add_i32 s19, s1, s19
	s_and_b32 s26, s19, 0xffffffc0
	s_sub_i32 s1, s1, s26
	s_lshl_b32 s19, s19, 4
	s_lshl_b32 s26, s1, 7
	s_and_b32 s19, s19, 0xfffffc00
	s_and_b32 s26, s26, 0x380
	s_lshl_b32 s1, s1, 4
	s_or_b32 s26, s26, s19
	s_and_b32 s28, s1, 0xffffff80
	s_ashr_i32 s27, s26, 31
	s_ashr_i32 s29, s28, 31
	s_lshl_b64 s[56:57], s[26:27], 10
	s_lshl_b64 s[52:53], s[28:29], 10
	v_readlane_b32 s28, v252, 50
	v_readlane_b32 s29, v252, 51

.Ltr_done_1055:
	s_cmp_lt_i32 s3, s23
	s_cselect_b64 s[40:41], -1, 0
	s_cmp_ge_i32 s3, s23
	s_cselect_b64 s[34:35], -1, 0
	s_mov_b64 s[42:43], 0
	s_and_b64 vcc, exec, s[34:35]
	s_mov_b64 s[44:45], 0
	s_mov_b64 s[46:47], 0
	s_cbranch_vccnz .LBB0_1057
	s_and_b32 s1, s3, 7
	s_mul_i32 s1, s1, s2
	s_ashr_i32 s19, s3, 3
	s_add_i32 s1, s1, s19
	s_ashr_i32 s19, s1, 31
	s_lshr_b32 s19, s19, 26
	s_add_i32 s19, s1, s19
	s_and_b32 s22, s19, 0xffffffc0
	s_sub_i32 s1, s1, s22
	s_lshl_b32 s19, s19, 4
	s_lshl_b32 s22, s1, 7
	s_lshl_b32 s1, s1, 4
	s_and_b32 s19, s19, 0xfffffc00
	s_and_b32 s22, s22, 0x380
	s_and_b32 s1, s1, 0xffff80
	s_or_b32 s19, s22, s19
	s_mul_i32 s46, s1, 0xb00
	s_mul_hi_i32 s45, s19, 0xb00
	s_mul_i32 s44, s19, 0xb00
	s_ashr_i32 s47, s46, 31
